# counted lgkmcnt waits also in the 128x128 K-loops of the merge gate/branch GEMMs and layer-0 mlp2 (second-operand fragments read first, per-group waits)
# baseline (speedup 1.0000x reference)
.LBB0_853:
	s_setprio 1
	s_waitcnt lgkmcnt(3)
	v_mfma_f32_16x16x32_bf16 v[158:161], v[46:49], v[70:73], v[158:161]
	v_mfma_f32_16x16x32_bf16 v[154:157], v[50:53], v[70:73], v[154:157]
	v_mfma_f32_16x16x32_bf16 v[150:153], v[54:57], v[70:73], v[150:153]
	v_mfma_f32_16x16x32_bf16 v[146:149], v[58:61], v[70:73], v[146:149]
	s_waitcnt lgkmcnt(2)
	v_mfma_f32_16x16x32_bf16 v[142:145], v[46:49], v[62:65], v[142:145]
	v_mfma_f32_16x16x32_bf16 v[138:141], v[50:53], v[62:65], v[138:141]
	v_mfma_f32_16x16x32_bf16 v[134:137], v[54:57], v[62:65], v[134:137]
	v_mfma_f32_16x16x32_bf16 v[130:133], v[58:61], v[62:65], v[130:133]
	s_waitcnt lgkmcnt(1)
	v_mfma_f32_16x16x32_bf16 v[126:129], v[46:49], v[42:45], v[126:129]
	v_mfma_f32_16x16x32_bf16 v[122:125], v[50:53], v[42:45], v[122:125]
	v_mfma_f32_16x16x32_bf16 v[118:121], v[54:57], v[42:45], v[118:121]
	v_mfma_f32_16x16x32_bf16 v[114:117], v[58:61], v[42:45], v[114:117]
	s_waitcnt lgkmcnt(0)
	v_mfma_f32_16x16x32_bf16 v[110:113], v[46:49], v[38:41], v[110:113]
	v_mfma_f32_16x16x32_bf16 v[102:105], v[50:53], v[38:41], v[102:105]
	v_mfma_f32_16x16x32_bf16 v[66:69], v[54:57], v[38:41], v[66:69]
	v_mfma_f32_16x16x32_bf16 v[34:37], v[58:61], v[38:41], v[34:37]
	s_setprio 0
	s_add_i32 s11, s11, 1
	s_cmp_lg_u32 s11, 4
	s_cselect_b32 s11, s11, 0
	s_add_i32 s18, s18, 1
	s_add_u32 s14, s14, 64
	s_addc_u32 s15, s15, 0
	s_cmpk_lg_i32 s14, 0x800
	s_cbranch_scc0 .LBB0_864

.LBB0_862:
	s_lshl_b32 s26, s11, 14
	s_add_i32 s26, s26, 0
	v_add3_u32 v38, s26, v246, v247
	v_add3_u32 v58, s26, v245, v247
	s_waitcnt lgkmcnt(0)
	s_barrier
	ds_read_b128 v[46:49], v58 offset:8192
	ds_read_b128 v[50:53], v58 offset:9216
	ds_read_b128 v[54:57], v58 offset:10240
	ds_read_b128 v[58:61], v58 offset:11264
	ds_read_b128 v[70:73], v38
	ds_read_b128 v[62:65], v38 offset:1024
	ds_read_b128 v[42:45], v38 offset:2048
	ds_read_b128 v[38:41], v38 offset:3072
	s_cmp_gt_u32 s18, 28
	s_cbranch_scc1 .LBB0_853
	s_cmp_gt_i32 s11, 0
	s_cselect_b32 s26, -1, 3
	s_add_i32 s26, s26, s11
	s_lshl_b32 s28, s26, 14
	v_lshl_add_u64 v[76:77], v[226:227], 0, s[14:15]
	s_mov_b64 s[26:27], 0x54600c0
	s_add_i32 s28, s10, s28
	v_lshl_add_u64 v[78:79], v[76:77], 0, s[26:27]
	s_mov_b32 m0, s28
	s_mov_b64 s[26:27], 0x54800c0
	global_load_lds_dwordx4 v[78:79], off
	v_lshl_add_u64 v[76:77], v[76:77], 0, s[26:27]
	s_add_i32 m0, s28, 0x1000
	s_mov_b64 s[26:27], 0xbc00c0
	global_load_lds_dwordx4 v[76:77], off
	v_lshl_add_u64 v[76:77], v[74:75], 0, s[14:15]
	v_lshl_add_u64 v[78:79], v[76:77], 0, s[26:27]
	s_add_i32 m0, s28, 0x2000
	s_mov_b64 s[26:27], 0xbe00c0
	global_load_lds_dwordx4 v[78:79], off
	v_lshl_add_u64 v[76:77], v[76:77], 0, s[26:27]
	s_add_i32 m0, s28, 0x3000
	s_nop 0
	global_load_lds_dwordx4 v[76:77], off
	s_branch .LBB0_853

.LBB0_865:
	s_setprio 1
	s_waitcnt lgkmcnt(3)
	v_mfma_f32_16x16x32_bf16 v[106:109], v[170:173], v[190:193], v[106:109]
	v_mfma_f32_16x16x32_bf16 v[98:101], v[174:177], v[190:193], v[98:101]
	v_mfma_f32_16x16x32_bf16 v[94:97], v[178:181], v[190:193], v[94:97]
	v_mfma_f32_16x16x32_bf16 v[90:93], v[182:185], v[190:193], v[90:93]
	s_waitcnt lgkmcnt(2)
	v_mfma_f32_16x16x32_bf16 v[86:89], v[170:173], v[186:189], v[86:89]
	v_mfma_f32_16x16x32_bf16 v[82:85], v[174:177], v[186:189], v[82:85]
	v_mfma_f32_16x16x32_bf16 v[78:81], v[178:181], v[186:189], v[78:81]
	v_mfma_f32_16x16x32_bf16 v[74:77], v[182:185], v[186:189], v[74:77]
	s_waitcnt lgkmcnt(1)
	v_mfma_f32_16x16x32_bf16 v[70:73], v[170:173], v[166:169], v[70:73]
	v_mfma_f32_16x16x32_bf16 v[62:65], v[174:177], v[166:169], v[62:65]
	v_mfma_f32_16x16x32_bf16 v[58:61], v[178:181], v[166:169], v[58:61]
	v_mfma_f32_16x16x32_bf16 v[54:57], v[182:185], v[166:169], v[54:57]
	s_waitcnt lgkmcnt(0)
	v_mfma_f32_16x16x32_bf16 v[50:53], v[170:173], v[162:165], v[50:53]
	v_mfma_f32_16x16x32_bf16 v[46:49], v[174:177], v[162:165], v[46:49]
	v_mfma_f32_16x16x32_bf16 v[42:45], v[178:181], v[162:165], v[42:45]
	v_mfma_f32_16x16x32_bf16 v[38:41], v[182:185], v[162:165], v[38:41]
	s_setprio 0
	s_add_i32 s11, s11, 1
	s_cmp_lg_u32 s11, 4
	s_cselect_b32 s11, s11, 0
	s_add_i32 s14, s14, 1
	s_add_u32 s6, s6, 64
	s_addc_u32 s7, s7, 0
	s_cmpk_lg_i32 s6, 0x400
	s_cbranch_scc0 .LBB0_843

.LBB0_874:
	s_lshl_b32 s12, s11, 14
	s_add_i32 s12, s12, 0
	v_add3_u32 v162, s12, v246, v247
	v_add3_u32 v182, s12, v245, v247
	s_waitcnt lgkmcnt(0)
	s_barrier
	ds_read_b128 v[170:173], v182 offset:8192
	ds_read_b128 v[174:177], v182 offset:9216
	ds_read_b128 v[178:181], v182 offset:10240
	ds_read_b128 v[182:185], v182 offset:11264
	ds_read_b128 v[190:193], v162
	ds_read_b128 v[186:189], v162 offset:1024
	ds_read_b128 v[166:169], v162 offset:2048
	ds_read_b128 v[162:165], v162 offset:3072
	s_cmp_gt_u32 s14, 12
	s_cbranch_scc1 .LBB0_865
	s_cmp_gt_i32 s11, 0
	s_cselect_b32 s12, -1, 3
	s_add_i32 s12, s12, s11
	s_lshl_b32 s12, s12, 14
	v_lshl_add_u64 v[248:249], v[232:233], 0, s[6:7]
	s_add_i32 s15, s10, s12
	v_lshl_add_u64 v[250:251], v[248:249], 0, s[36:37]
	s_mov_b32 m0, s15
	s_mov_b64 s[12:13], 0x78fc0c0
	global_load_lds_dwordx4 v[250:251], off
	v_lshl_add_u64 v[248:249], v[248:249], 0, s[12:13]
	s_add_i32 m0, s15, 0x1000
	s_mov_b64 s[12:13], 0x15300c0
	global_load_lds_dwordx4 v[248:249], off
	v_lshl_add_u64 v[248:249], v[230:231], 0, s[6:7]
	v_lshl_add_u64 v[250:251], v[248:249], 0, s[12:13]
	s_add_i32 m0, s15, 0x2000
	s_mov_b64 s[12:13], 0x15400c0
	global_load_lds_dwordx4 v[250:251], off
	v_lshl_add_u64 v[248:249], v[248:249], 0, s[12:13]
	s_add_i32 m0, s15, 0x3000
	s_nop 0
	global_load_lds_dwordx4 v[248:249], off
	s_branch .LBB0_865

.LBB0_1206:
	s_setprio 1
	s_waitcnt lgkmcnt(3)
	v_mfma_f32_16x16x32_bf16 v[62:65], v[74:77], v[94:97], v[62:65]
	v_mfma_f32_16x16x32_bf16 v[58:61], v[78:81], v[94:97], v[58:61]
	v_mfma_f32_16x16x32_bf16 v[54:57], v[82:85], v[94:97], v[54:57]
	v_mfma_f32_16x16x32_bf16 v[50:53], v[86:89], v[94:97], v[50:53]
	s_waitcnt lgkmcnt(2)
	v_mfma_f32_16x16x32_bf16 v[46:49], v[74:77], v[90:93], v[46:49]
	v_mfma_f32_16x16x32_bf16 v[42:45], v[78:81], v[90:93], v[42:45]
	v_mfma_f32_16x16x32_bf16 v[38:41], v[82:85], v[90:93], v[38:41]
	v_mfma_f32_16x16x32_bf16 v[34:37], v[86:89], v[90:93], v[34:37]
	s_waitcnt lgkmcnt(1)
	v_mfma_f32_16x16x32_bf16 v[30:33], v[74:77], v[70:73], v[30:33]
	v_mfma_f32_16x16x32_bf16 v[26:29], v[78:81], v[70:73], v[26:29]
	v_mfma_f32_16x16x32_bf16 v[22:25], v[82:85], v[70:73], v[22:25]
	v_mfma_f32_16x16x32_bf16 v[18:21], v[86:89], v[70:73], v[18:21]
	s_waitcnt lgkmcnt(0)
	v_mfma_f32_16x16x32_bf16 v[14:17], v[74:77], v[66:69], v[14:17]
	v_mfma_f32_16x16x32_bf16 v[10:13], v[78:81], v[66:69], v[10:13]
	v_mfma_f32_16x16x32_bf16 v[6:9], v[82:85], v[66:69], v[6:9]
	v_mfma_f32_16x16x32_bf16 v[2:5], v[86:89], v[66:69], v[2:5]
	s_setprio 0
	s_add_i32 s3, s3, 1
	s_cmp_lg_u32 s3, 4
	s_cselect_b32 s3, s3, 0
	s_add_i32 s7, s7, 1
	s_add_u32 s14, s14, 64
	s_addc_u32 s15, s15, 0
	s_cmpk_lg_i32 s14, 0x2000
	s_cbranch_scc0 .LBB0_1217

.LBB0_1215:
	s_lshl_b32 s10, s3, 14
	s_add_i32 s10, s10, 0
	v_add3_u32 v66, s10, v112, v113
	v_add3_u32 v86, s10, v111, v113
	s_waitcnt lgkmcnt(0)
	s_barrier
	ds_read_b128 v[74:77], v86 offset:8192
	ds_read_b128 v[78:81], v86 offset:9216
	ds_read_b128 v[82:85], v86 offset:10240
	ds_read_b128 v[86:89], v86 offset:11264
	ds_read_b128 v[94:97], v66
	ds_read_b128 v[90:93], v66 offset:1024
	ds_read_b128 v[70:73], v66 offset:2048
	ds_read_b128 v[66:69], v66 offset:3072
	s_cmpk_gt_u32 s7, 0x7c
	s_cbranch_scc1 .LBB0_1206
	s_cmp_gt_i32 s3, 0
	s_cselect_b32 s10, -1, 3
	s_add_i32 s10, s10, s3
	s_lshl_b32 s10, s10, 14
	v_lshl_add_u64 v[116:117], v[108:109], 0, s[14:15]
	s_add_i32 s13, s2, s10
	v_lshl_add_u64 v[118:119], v[116:117], 0, s[36:37]
	s_mov_b32 m0, s13
	s_mov_b64 s[10:11], 0x78e00c0
	global_load_lds_dwordx4 v[118:119], off
	v_lshl_add_u64 v[116:117], v[116:117], 0, s[10:11]
	s_add_i32 m0, s13, 0x1000
	s_mov_b64 s[10:11], 0x23300c0
	global_load_lds_dwordx4 v[116:117], off
	v_lshl_add_u64 v[116:117], v[106:107], 0, s[14:15]
	v_lshl_add_u64 v[118:119], v[116:117], 0, s[10:11]
	s_add_i32 m0, s13, 0x2000
	s_mov_b64 s[10:11], 0x23b00c0
	global_load_lds_dwordx4 v[118:119], off
	v_lshl_add_u64 v[116:117], v[116:117], 0, s[10:11]
	s_add_i32 m0, s13, 0x3000
	s_nop 0
	global_load_lds_dwordx4 v[116:117], off
	s_branch .LBB0_1206
